# GEMM K-loops: LDS-DMA sources as SGPR base + lane offset (no address VALU); the last piece of super-phase 1 is requested at the start of super-phase 2 (2,5,3,6 pieces; vmcnt(7) there)
# speedup vs baseline: 1.0129x; 1.0019x over previous
.LBB0_367:
	ds_read_b128 v[130:133], v168
	ds_read_b128 v[134:137], v168 offset:1024
	ds_read_b128 v[138:141], v168 offset:2048
	ds_read_b128 v[142:145], v168 offset:3072
	ds_read_b128 v[172:175], v169
	ds_read_b128 v[176:179], v169 offset:1024
	ds_read_b128 v[180:183], v169 offset:2048
	ds_read_b128 v[184:187], v169 offset:3072
	s_add_u32 s36, s34, 0xfffc0080
	s_addc_u32 s37, s35, -1
	s_cmp_eq_u32 s65, 12
	s_cselect_b32 s39, s1, s37
	s_cselect_b32 s38, s25, s36
	s_cselect_b32 s37, s23, s41
	s_cselect_b32 s36, s31, s40
	s_add_u32 s70, s38, 0x80
	s_addc_u32 s71, s39, 0
	s_add_i32 m0, s47, 0xc000
	ds_read_b128 v[188:191], v170
	ds_read_b128 v[192:195], v170 offset:1024
	ds_read_b128 v[196:199], v170 offset:2048
	ds_read_b128 v[200:203], v170 offset:3072
	ds_read_b128 v[204:207], v170 offset:4096
	ds_read_b128 v[208:211], v170 offset:5120
	ds_read_b128 v[212:215], v170 offset:6144
	ds_read_b128 v[216:219], v170 offset:7168
	global_load_lds_dwordx4 v158, s[34:35]
	s_add_i32 m0, s47, 0xe000
	s_nop 0
	global_load_lds_dwordx4 v160, s[34:35]
	s_waitcnt vmcnt(8)
	s_waitcnt lgkmcnt(0)
	s_barrier
	s_setprio 1
	s_waitcnt lgkmcnt(0)
	v_mfma_f32_16x16x32_bf16 v[126:129], v[130:133], v[188:191], v[126:129]
	v_mfma_f32_16x16x32_bf16 v[122:125], v[138:141], v[188:191], v[122:125]
	v_mfma_f32_16x16x32_bf16 v[110:113], v[130:133], v[196:199], v[110:113]
	v_mfma_f32_16x16x32_bf16 v[106:109], v[138:141], v[196:199], v[106:109]
	v_mfma_f32_16x16x32_bf16 v[94:97], v[130:133], v[204:207], v[94:97]
	v_mfma_f32_16x16x32_bf16 v[90:93], v[138:141], v[204:207], v[90:93]
	v_mfma_f32_16x16x32_bf16 v[78:81], v[130:133], v[212:215], v[78:81]
	v_mfma_f32_16x16x32_bf16 v[74:77], v[138:141], v[212:215], v[74:77]
	v_mfma_f32_16x16x32_bf16 v[126:129], v[134:137], v[192:195], v[126:129]
	v_mfma_f32_16x16x32_bf16 v[122:125], v[142:145], v[192:195], v[122:125]
	v_mfma_f32_16x16x32_bf16 v[110:113], v[134:137], v[200:203], v[110:113]
	v_mfma_f32_16x16x32_bf16 v[106:109], v[142:145], v[200:203], v[106:109]
	v_mfma_f32_16x16x32_bf16 v[94:97], v[134:137], v[208:211], v[94:97]
	v_mfma_f32_16x16x32_bf16 v[90:93], v[142:145], v[208:211], v[90:93]
	v_mfma_f32_16x16x32_bf16 v[78:81], v[134:137], v[216:219], v[78:81]
	v_mfma_f32_16x16x32_bf16 v[74:77], v[142:145], v[216:219], v[74:77]
	s_setprio 0
	s_setprio 1
	v_mfma_f32_16x16x32_bf16 v[118:121], v[172:175], v[188:191], v[118:121]
	v_mfma_f32_16x16x32_bf16 v[114:117], v[180:183], v[188:191], v[114:117]
	v_mfma_f32_16x16x32_bf16 v[102:105], v[172:175], v[196:199], v[102:105]
	v_mfma_f32_16x16x32_bf16 v[98:101], v[180:183], v[196:199], v[98:101]
	v_mfma_f32_16x16x32_bf16 v[86:89], v[172:175], v[204:207], v[86:89]
	v_mfma_f32_16x16x32_bf16 v[82:85], v[180:183], v[204:207], v[82:85]
	v_mfma_f32_16x16x32_bf16 v[70:73], v[172:175], v[212:215], v[70:73]
	v_mfma_f32_16x16x32_bf16 v[66:69], v[180:183], v[212:215], v[66:69]
	v_mfma_f32_16x16x32_bf16 v[118:121], v[176:179], v[192:195], v[118:121]
	v_mfma_f32_16x16x32_bf16 v[114:117], v[184:187], v[192:195], v[114:117]
	v_mfma_f32_16x16x32_bf16 v[102:105], v[176:179], v[200:203], v[102:105]
	v_mfma_f32_16x16x32_bf16 v[98:101], v[184:187], v[200:203], v[98:101]
	v_mfma_f32_16x16x32_bf16 v[86:89], v[176:179], v[208:211], v[86:89]
	v_mfma_f32_16x16x32_bf16 v[82:85], v[184:187], v[208:211], v[82:85]
	v_mfma_f32_16x16x32_bf16 v[70:73], v[176:179], v[216:219], v[70:73]
	v_mfma_f32_16x16x32_bf16 v[66:69], v[184:187], v[216:219], v[66:69]
	s_setprio 0
	s_barrier
	s_add_i32 s66, s61, s46
	s_mov_b32 m0, s66
	ds_read_b128 v[188:191], v170 offset:16384
	ds_read_b128 v[192:195], v170 offset:17408
	ds_read_b128 v[196:199], v170 offset:18432
	ds_read_b128 v[200:203], v170 offset:19456
	ds_read_b128 v[204:207], v170 offset:20480
	ds_read_b128 v[208:211], v170 offset:21504
	ds_read_b128 v[212:215], v170 offset:22528
	ds_read_b128 v[216:219], v170 offset:23552
	global_load_lds_dwordx4 v148, s[36:37]
	s_add_i32 m0, s66, 0x2000
	s_add_u32 s66, s36, 0x10000
	s_addc_u32 s67, s37, 0
	s_add_i32 s68, s62, s46
	global_load_lds_dwordx4 v152, s[36:37]
	s_mov_b32 m0, s68
	s_nop 0
	global_load_lds_dwordx4 v148, s[66:67]
	s_add_i32 m0, s68, 0x2000
	s_nop 0
	global_load_lds_dwordx4 v152, s[66:67]
	s_mov_b32 m0, s47
	s_nop 0
	global_load_lds_dwordx4 v146, s[38:39]
	s_waitcnt vmcnt(7)
	s_waitcnt lgkmcnt(0)
	s_barrier
	s_setprio 1
	s_waitcnt lgkmcnt(0)
	v_mfma_f32_16x16x32_bf16 v[62:65], v[130:133], v[188:191], v[62:65]
	v_mfma_f32_16x16x32_bf16 v[58:61], v[138:141], v[188:191], v[58:61]
	v_mfma_f32_16x16x32_bf16 v[46:49], v[130:133], v[196:199], v[46:49]
	v_mfma_f32_16x16x32_bf16 v[42:45], v[138:141], v[196:199], v[42:45]
	v_mfma_f32_16x16x32_bf16 v[30:33], v[130:133], v[204:207], v[30:33]
	v_mfma_f32_16x16x32_bf16 v[26:29], v[138:141], v[204:207], v[26:29]
	v_mfma_f32_16x16x32_bf16 v[14:17], v[130:133], v[212:215], v[14:17]
	v_mfma_f32_16x16x32_bf16 v[10:13], v[138:141], v[212:215], v[10:13]
	v_mfma_f32_16x16x32_bf16 v[62:65], v[134:137], v[192:195], v[62:65]
	v_mfma_f32_16x16x32_bf16 v[58:61], v[142:145], v[192:195], v[58:61]
	v_mfma_f32_16x16x32_bf16 v[46:49], v[134:137], v[200:203], v[46:49]
	v_mfma_f32_16x16x32_bf16 v[42:45], v[142:145], v[200:203], v[42:45]
	v_mfma_f32_16x16x32_bf16 v[30:33], v[134:137], v[208:211], v[30:33]
	v_mfma_f32_16x16x32_bf16 v[26:29], v[142:145], v[208:211], v[26:29]
	v_mfma_f32_16x16x32_bf16 v[14:17], v[134:137], v[216:219], v[14:17]
	v_mfma_f32_16x16x32_bf16 v[10:13], v[142:145], v[216:219], v[10:13]
	s_setprio 0
	s_setprio 1
	v_mfma_f32_16x16x32_bf16 v[54:57], v[172:175], v[188:191], v[54:57]
	v_mfma_f32_16x16x32_bf16 v[50:53], v[180:183], v[188:191], v[50:53]
	v_mfma_f32_16x16x32_bf16 v[38:41], v[172:175], v[196:199], v[38:41]
	v_mfma_f32_16x16x32_bf16 v[34:37], v[180:183], v[196:199], v[34:37]
	v_mfma_f32_16x16x32_bf16 v[22:25], v[172:175], v[204:207], v[22:25]
	v_mfma_f32_16x16x32_bf16 v[18:21], v[180:183], v[204:207], v[18:21]
	v_mfma_f32_16x16x32_bf16 v[6:9], v[172:175], v[212:215], v[6:9]
	v_mfma_f32_16x16x32_bf16 v[2:5], v[180:183], v[212:215], v[2:5]
	v_mfma_f32_16x16x32_bf16 v[54:57], v[176:179], v[192:195], v[54:57]
	v_mfma_f32_16x16x32_bf16 v[50:53], v[184:187], v[192:195], v[50:53]
	v_mfma_f32_16x16x32_bf16 v[38:41], v[176:179], v[200:203], v[38:41]
	v_mfma_f32_16x16x32_bf16 v[34:37], v[184:187], v[200:203], v[34:37]
	v_mfma_f32_16x16x32_bf16 v[22:25], v[176:179], v[208:211], v[22:25]
	v_mfma_f32_16x16x32_bf16 v[18:21], v[184:187], v[208:211], v[18:21]
	v_mfma_f32_16x16x32_bf16 v[6:9], v[176:179], v[216:219], v[6:9]
	v_mfma_f32_16x16x32_bf16 v[2:5], v[184:187], v[216:219], v[2:5]
	s_setprio 0
	s_barrier
	s_add_i32 s66, 0, 0x18000
	s_add_i32 s67, 0, 0x1c000
	v_add_u32_e32 v142, s66, v157
	v_add_u32_e32 v154, s67, v157
	ds_read_b128 v[130:133], v142
	ds_read_b128 v[134:137], v142 offset:1024
	ds_read_b128 v[138:141], v142 offset:2048
	ds_read_b128 v[142:145], v142 offset:3072
	ds_read_b128 v[172:175], v154
	ds_read_b128 v[176:179], v154 offset:1024
	ds_read_b128 v[180:183], v154 offset:2048
	ds_read_b128 v[184:187], v154 offset:3072
	s_mov_b32 m0, s48
	s_nop 0
	global_load_lds_dwordx4 v150, s[38:39]
	s_add_u32 s38, s38, 0x40000
	s_addc_u32 s39, s39, 0
	s_mov_b32 m0, s49
	ds_read_b128 v[188:191], v170 offset:32768
	ds_read_b128 v[192:195], v170 offset:33792
	ds_read_b128 v[196:199], v170 offset:34816
	ds_read_b128 v[200:203], v170 offset:35840
	ds_read_b128 v[204:207], v170 offset:36864
	ds_read_b128 v[208:211], v170 offset:37888
	ds_read_b128 v[212:215], v170 offset:38912
	ds_read_b128 v[216:219], v170 offset:39936
	global_load_lds_dwordx4 v146, s[38:39]
	s_mov_b32 m0, s50
	s_nop 0
	global_load_lds_dwordx4 v150, s[38:39]
	s_waitcnt vmcnt(8)
	s_waitcnt lgkmcnt(0)
	s_barrier
	s_setprio 1
	s_waitcnt lgkmcnt(0)
	v_mfma_f32_16x16x32_bf16 v[126:129], v[130:133], v[188:191], v[126:129]
	v_mfma_f32_16x16x32_bf16 v[122:125], v[138:141], v[188:191], v[122:125]
	v_mfma_f32_16x16x32_bf16 v[110:113], v[130:133], v[196:199], v[110:113]
	v_mfma_f32_16x16x32_bf16 v[106:109], v[138:141], v[196:199], v[106:109]
	v_mfma_f32_16x16x32_bf16 v[94:97], v[130:133], v[204:207], v[94:97]
	v_mfma_f32_16x16x32_bf16 v[90:93], v[138:141], v[204:207], v[90:93]
	v_mfma_f32_16x16x32_bf16 v[78:81], v[130:133], v[212:215], v[78:81]
	v_mfma_f32_16x16x32_bf16 v[74:77], v[138:141], v[212:215], v[74:77]
	v_mfma_f32_16x16x32_bf16 v[126:129], v[134:137], v[192:195], v[126:129]
	v_mfma_f32_16x16x32_bf16 v[122:125], v[142:145], v[192:195], v[122:125]
	v_mfma_f32_16x16x32_bf16 v[110:113], v[134:137], v[200:203], v[110:113]
	v_mfma_f32_16x16x32_bf16 v[106:109], v[142:145], v[200:203], v[106:109]
	v_mfma_f32_16x16x32_bf16 v[94:97], v[134:137], v[208:211], v[94:97]
	v_mfma_f32_16x16x32_bf16 v[90:93], v[142:145], v[208:211], v[90:93]
	v_mfma_f32_16x16x32_bf16 v[78:81], v[134:137], v[216:219], v[78:81]
	v_mfma_f32_16x16x32_bf16 v[74:77], v[142:145], v[216:219], v[74:77]
	s_setprio 0
	s_setprio 1
	v_mfma_f32_16x16x32_bf16 v[118:121], v[172:175], v[188:191], v[118:121]
	v_mfma_f32_16x16x32_bf16 v[114:117], v[180:183], v[188:191], v[114:117]
	v_mfma_f32_16x16x32_bf16 v[102:105], v[172:175], v[196:199], v[102:105]
	v_mfma_f32_16x16x32_bf16 v[98:101], v[180:183], v[196:199], v[98:101]
	v_mfma_f32_16x16x32_bf16 v[86:89], v[172:175], v[204:207], v[86:89]
	v_mfma_f32_16x16x32_bf16 v[82:85], v[180:183], v[204:207], v[82:85]
	v_mfma_f32_16x16x32_bf16 v[70:73], v[172:175], v[212:215], v[70:73]
	v_mfma_f32_16x16x32_bf16 v[66:69], v[180:183], v[212:215], v[66:69]
	v_mfma_f32_16x16x32_bf16 v[118:121], v[176:179], v[192:195], v[118:121]
	v_mfma_f32_16x16x32_bf16 v[114:117], v[184:187], v[192:195], v[114:117]
	v_mfma_f32_16x16x32_bf16 v[102:105], v[176:179], v[200:203], v[102:105]
	v_mfma_f32_16x16x32_bf16 v[98:101], v[184:187], v[200:203], v[98:101]
	v_mfma_f32_16x16x32_bf16 v[86:89], v[176:179], v[208:211], v[86:89]
	v_mfma_f32_16x16x32_bf16 v[82:85], v[184:187], v[208:211], v[82:85]
	v_mfma_f32_16x16x32_bf16 v[70:73], v[176:179], v[216:219], v[70:73]
	v_mfma_f32_16x16x32_bf16 v[66:69], v[184:187], v[216:219], v[66:69]
	s_setprio 0
	s_barrier
	s_add_i32 s38, s66, s46
	s_mov_b32 m0, s38
	ds_read_b128 v[188:191], v170 offset:49152
	ds_read_b128 v[192:195], v170 offset:50176
	ds_read_b128 v[196:199], v170 offset:51200
	ds_read_b128 v[200:203], v170 offset:52224
	ds_read_b128 v[204:207], v170 offset:53248
	ds_read_b128 v[208:211], v170 offset:54272
	ds_read_b128 v[212:215], v170 offset:55296
	ds_read_b128 v[216:219], v170 offset:56320
	s_add_u32 s36, s36, 0x80
	s_addc_u32 s37, s37, 0
	global_load_lds_dwordx4 v148, s[36:37]
	s_add_i32 m0, s38, 0x2000
	s_add_i32 s38, s67, s46
	global_load_lds_dwordx4 v152, s[36:37]
	s_add_u32 s36, s36, 0x10000
	s_addc_u32 s37, s37, 0
	s_mov_b32 m0, s38
	s_nop 0
	global_load_lds_dwordx4 v148, s[36:37]
	s_add_i32 m0, s38, 0x2000
	s_nop 0
	global_load_lds_dwordx4 v152, s[36:37]
	s_mov_b32 m0, s56
	s_nop 0
	global_load_lds_dwordx4 v146, s[70:71]
	s_mov_b32 m0, s57
	s_nop 0
	global_load_lds_dwordx4 v150, s[70:71]
	s_waitcnt vmcnt(8)
	s_waitcnt lgkmcnt(0)
	s_barrier
	s_setprio 1
	s_waitcnt lgkmcnt(0)
	v_mfma_f32_16x16x32_bf16 v[62:65], v[130:133], v[188:191], v[62:65]
	v_mfma_f32_16x16x32_bf16 v[58:61], v[138:141], v[188:191], v[58:61]
	v_mfma_f32_16x16x32_bf16 v[46:49], v[130:133], v[196:199], v[46:49]
	v_mfma_f32_16x16x32_bf16 v[42:45], v[138:141], v[196:199], v[42:45]
	v_mfma_f32_16x16x32_bf16 v[30:33], v[130:133], v[204:207], v[30:33]
	v_mfma_f32_16x16x32_bf16 v[26:29], v[138:141], v[204:207], v[26:29]
	v_mfma_f32_16x16x32_bf16 v[14:17], v[130:133], v[212:215], v[14:17]
	v_mfma_f32_16x16x32_bf16 v[10:13], v[138:141], v[212:215], v[10:13]
	v_mfma_f32_16x16x32_bf16 v[62:65], v[134:137], v[192:195], v[62:65]
	v_mfma_f32_16x16x32_bf16 v[58:61], v[142:145], v[192:195], v[58:61]
	v_mfma_f32_16x16x32_bf16 v[46:49], v[134:137], v[200:203], v[46:49]
	v_mfma_f32_16x16x32_bf16 v[42:45], v[142:145], v[200:203], v[42:45]
	v_mfma_f32_16x16x32_bf16 v[30:33], v[134:137], v[208:211], v[30:33]
	v_mfma_f32_16x16x32_bf16 v[26:29], v[142:145], v[208:211], v[26:29]
	v_mfma_f32_16x16x32_bf16 v[14:17], v[134:137], v[216:219], v[14:17]
	v_mfma_f32_16x16x32_bf16 v[10:13], v[142:145], v[216:219], v[10:13]
	s_setprio 0
	s_setprio 1
	v_mfma_f32_16x16x32_bf16 v[54:57], v[172:175], v[188:191], v[54:57]
	v_mfma_f32_16x16x32_bf16 v[50:53], v[180:183], v[188:191], v[50:53]
	v_mfma_f32_16x16x32_bf16 v[38:41], v[172:175], v[196:199], v[38:41]
	v_mfma_f32_16x16x32_bf16 v[34:37], v[180:183], v[196:199], v[34:37]
	v_mfma_f32_16x16x32_bf16 v[22:25], v[172:175], v[204:207], v[22:25]
	s_add_i32 s65, s65, 2
	v_mfma_f32_16x16x32_bf16 v[18:21], v[180:183], v[204:207], v[18:21]
	v_mfma_f32_16x16x32_bf16 v[6:9], v[172:175], v[212:215], v[6:9]
	s_add_u32 s34, s34, 0x100
	s_addc_u32 s35, s35, 0
	v_mfma_f32_16x16x32_bf16 v[2:5], v[180:183], v[212:215], v[2:5]
	v_mfma_f32_16x16x32_bf16 v[54:57], v[176:179], v[192:195], v[54:57]
	s_add_u32 s40, s40, 0x100
	s_addc_u32 s41, s41, 0
	v_mfma_f32_16x16x32_bf16 v[50:53], v[184:187], v[192:195], v[50:53]
	v_mfma_f32_16x16x32_bf16 v[38:41], v[176:179], v[200:203], v[38:41]
	s_cmp_gt_u32 s65, 13
	v_mfma_f32_16x16x32_bf16 v[34:37], v[184:187], v[200:203], v[34:37]
	v_mfma_f32_16x16x32_bf16 v[22:25], v[176:179], v[208:211], v[22:25]
	v_mfma_f32_16x16x32_bf16 v[18:21], v[184:187], v[208:211], v[18:21]
	v_mfma_f32_16x16x32_bf16 v[6:9], v[176:179], v[216:219], v[6:9]
	v_mfma_f32_16x16x32_bf16 v[2:5], v[184:187], v[216:219], v[2:5]
	s_setprio 0
	s_barrier
	s_cbranch_scc0 .LBB0_367
	s_and_b64 vcc, exec, s[20:21]
	s_cbranch_vccz .LBB0_370
	s_barrier

.LBB0_766:
	ds_read_b128 v[128:131], v163
	ds_read_b128 v[132:135], v163 offset:1024
	ds_read_b128 v[136:139], v163 offset:2048
	ds_read_b128 v[140:143], v163 offset:3072
	ds_read_b128 v[156:159], v164
	ds_read_b128 v[166:169], v164 offset:1024
	ds_read_b128 v[170:173], v164 offset:2048
	ds_read_b128 v[174:177], v164 offset:3072
	s_add_u32 s38, s36, 0xfffc0080
	s_addc_u32 s39, s37, -1
	s_cmp_eq_u32 s63, 12
	s_cselect_b32 s41, s27, s39
	s_cselect_b32 s40, s59, s38
	s_cselect_b32 s39, s25, s62
	s_cselect_b32 s38, s60, s61
	s_add_u32 s68, s40, 0x80
	s_addc_u32 s69, s41, 0
	s_add_i32 m0, s35, 0xc000
	ds_read_b128 v[178:181], v165
	ds_read_b128 v[182:185], v165 offset:1024
	ds_read_b128 v[186:189], v165 offset:2048
	ds_read_b128 v[190:193], v165 offset:3072
	ds_read_b128 v[194:197], v165 offset:4096
	ds_read_b128 v[198:201], v165 offset:5120
	ds_read_b128 v[202:205], v165 offset:6144
	ds_read_b128 v[206:209], v165 offset:7168
	global_load_lds_dwordx4 v148, s[36:37]
	s_add_i32 m0, s35, 0xe000
	s_nop 0
	global_load_lds_dwordx4 v150, s[36:37]
	s_waitcnt vmcnt(8)
	s_waitcnt lgkmcnt(0)
	s_barrier
	s_setprio 1
	s_waitcnt lgkmcnt(0)
	v_mfma_f32_16x16x32_bf16 v[124:127], v[128:131], v[178:181], v[124:127]
	v_mfma_f32_16x16x32_bf16 v[120:123], v[136:139], v[178:181], v[120:123]
	v_mfma_f32_16x16x32_bf16 v[116:119], v[128:131], v[186:189], v[116:119]
	v_mfma_f32_16x16x32_bf16 v[108:111], v[136:139], v[186:189], v[108:111]
	v_mfma_f32_16x16x32_bf16 v[96:99], v[128:131], v[194:197], v[96:99]
	v_mfma_f32_16x16x32_bf16 v[88:91], v[136:139], v[194:197], v[88:91]
	v_mfma_f32_16x16x32_bf16 v[84:87], v[128:131], v[202:205], v[84:87]
	v_mfma_f32_16x16x32_bf16 v[76:79], v[136:139], v[202:205], v[76:79]
	v_mfma_f32_16x16x32_bf16 v[124:127], v[132:135], v[182:185], v[124:127]
	v_mfma_f32_16x16x32_bf16 v[120:123], v[140:143], v[182:185], v[120:123]
	v_mfma_f32_16x16x32_bf16 v[116:119], v[132:135], v[190:193], v[116:119]
	v_mfma_f32_16x16x32_bf16 v[108:111], v[140:143], v[190:193], v[108:111]
	v_mfma_f32_16x16x32_bf16 v[96:99], v[132:135], v[198:201], v[96:99]
	v_mfma_f32_16x16x32_bf16 v[88:91], v[140:143], v[198:201], v[88:91]
	v_mfma_f32_16x16x32_bf16 v[84:87], v[132:135], v[206:209], v[84:87]
	v_mfma_f32_16x16x32_bf16 v[76:79], v[140:143], v[206:209], v[76:79]
	s_setprio 0
	s_setprio 1
	v_mfma_f32_16x16x32_bf16 v[112:115], v[156:159], v[178:181], v[112:115]
	v_mfma_f32_16x16x32_bf16 v[104:107], v[170:173], v[178:181], v[104:107]
	v_mfma_f32_16x16x32_bf16 v[100:103], v[156:159], v[186:189], v[100:103]
	v_mfma_f32_16x16x32_bf16 v[92:95], v[170:173], v[186:189], v[92:95]
	v_mfma_f32_16x16x32_bf16 v[80:83], v[156:159], v[194:197], v[80:83]
	v_mfma_f32_16x16x32_bf16 v[72:75], v[170:173], v[194:197], v[72:75]
	v_mfma_f32_16x16x32_bf16 v[68:71], v[156:159], v[202:205], v[68:71]
	v_mfma_f32_16x16x32_bf16 v[64:67], v[170:173], v[202:205], v[64:67]
	v_mfma_f32_16x16x32_bf16 v[112:115], v[166:169], v[182:185], v[112:115]
	v_mfma_f32_16x16x32_bf16 v[104:107], v[174:177], v[182:185], v[104:107]
	v_mfma_f32_16x16x32_bf16 v[100:103], v[166:169], v[190:193], v[100:103]
	v_mfma_f32_16x16x32_bf16 v[92:95], v[174:177], v[190:193], v[92:95]
	v_mfma_f32_16x16x32_bf16 v[80:83], v[166:169], v[198:201], v[80:83]
	v_mfma_f32_16x16x32_bf16 v[72:75], v[174:177], v[198:201], v[72:75]
	v_mfma_f32_16x16x32_bf16 v[68:71], v[166:169], v[206:209], v[68:71]
	v_mfma_f32_16x16x32_bf16 v[64:67], v[174:177], v[206:209], v[64:67]
	s_setprio 0
	s_barrier
	s_add_i32 s64, s55, s46
	s_mov_b32 m0, s64
	ds_read_b128 v[178:181], v165 offset:16384
	ds_read_b128 v[182:185], v165 offset:17408
	ds_read_b128 v[186:189], v165 offset:18432
	ds_read_b128 v[190:193], v165 offset:19456
	ds_read_b128 v[194:197], v165 offset:20480
	ds_read_b128 v[198:201], v165 offset:21504
	ds_read_b128 v[202:205], v165 offset:22528
	ds_read_b128 v[206:209], v165 offset:23552
	global_load_lds_dwordx4 v144, s[38:39]
	s_add_i32 m0, s64, 0x2000
	s_add_u32 s64, s38, 0x40000
	s_addc_u32 s65, s39, 0
	s_add_i32 s66, s56, s46
	global_load_lds_dwordx4 v146, s[38:39]
	s_mov_b32 m0, s66
	s_nop 0
	global_load_lds_dwordx4 v144, s[64:65]
	s_add_i32 m0, s66, 0x2000
	s_nop 0
	global_load_lds_dwordx4 v146, s[64:65]
	s_mov_b32 m0, s35
	s_nop 0
	global_load_lds_dwordx4 v144, s[40:41]
	s_waitcnt vmcnt(7)
	s_waitcnt lgkmcnt(0)
	s_barrier
	s_setprio 1
	s_waitcnt lgkmcnt(0)
	v_mfma_f32_16x16x32_bf16 v[60:63], v[128:131], v[178:181], v[60:63]
	v_mfma_f32_16x16x32_bf16 v[56:59], v[136:139], v[178:181], v[56:59]
	v_mfma_f32_16x16x32_bf16 v[52:55], v[128:131], v[186:189], v[52:55]
	v_mfma_f32_16x16x32_bf16 v[44:47], v[136:139], v[186:189], v[44:47]
	v_mfma_f32_16x16x32_bf16 v[36:39], v[128:131], v[194:197], v[36:39]
	v_mfma_f32_16x16x32_bf16 v[28:31], v[136:139], v[194:197], v[28:31]
	v_mfma_f32_16x16x32_bf16 v[20:23], v[128:131], v[202:205], v[20:23]
	v_mfma_f32_16x16x32_bf16 v[12:15], v[136:139], v[202:205], v[12:15]
	v_mfma_f32_16x16x32_bf16 v[60:63], v[132:135], v[182:185], v[60:63]
	v_mfma_f32_16x16x32_bf16 v[56:59], v[140:143], v[182:185], v[56:59]
	v_mfma_f32_16x16x32_bf16 v[52:55], v[132:135], v[190:193], v[52:55]
	v_mfma_f32_16x16x32_bf16 v[44:47], v[140:143], v[190:193], v[44:47]
	v_mfma_f32_16x16x32_bf16 v[36:39], v[132:135], v[198:201], v[36:39]
	v_mfma_f32_16x16x32_bf16 v[28:31], v[140:143], v[198:201], v[28:31]
	v_mfma_f32_16x16x32_bf16 v[20:23], v[132:135], v[206:209], v[20:23]
	v_mfma_f32_16x16x32_bf16 v[12:15], v[140:143], v[206:209], v[12:15]
	s_setprio 0
	s_setprio 1
	v_mfma_f32_16x16x32_bf16 v[48:51], v[156:159], v[178:181], v[48:51]
	v_mfma_f32_16x16x32_bf16 v[40:43], v[170:173], v[178:181], v[40:43]
	v_mfma_f32_16x16x32_bf16 v[32:35], v[156:159], v[186:189], v[32:35]
	v_mfma_f32_16x16x32_bf16 v[24:27], v[170:173], v[186:189], v[24:27]
	v_mfma_f32_16x16x32_bf16 v[16:19], v[156:159], v[194:197], v[16:19]
	v_mfma_f32_16x16x32_bf16 v[8:11], v[170:173], v[194:197], v[8:11]
	v_mfma_f32_16x16x32_bf16 v[4:7], v[156:159], v[202:205], v[4:7]
	v_mfma_f32_16x16x32_bf16 v[0:3], v[170:173], v[202:205], v[0:3]
	v_mfma_f32_16x16x32_bf16 v[48:51], v[166:169], v[182:185], v[48:51]
	v_mfma_f32_16x16x32_bf16 v[40:43], v[174:177], v[182:185], v[40:43]
	v_mfma_f32_16x16x32_bf16 v[32:35], v[166:169], v[190:193], v[32:35]
	v_mfma_f32_16x16x32_bf16 v[24:27], v[174:177], v[190:193], v[24:27]
	v_mfma_f32_16x16x32_bf16 v[16:19], v[166:169], v[198:201], v[16:19]
	v_mfma_f32_16x16x32_bf16 v[8:11], v[174:177], v[198:201], v[8:11]
	v_mfma_f32_16x16x32_bf16 v[4:7], v[166:169], v[206:209], v[4:7]
	v_mfma_f32_16x16x32_bf16 v[0:3], v[174:177], v[206:209], v[0:3]
	s_setprio 0
	s_barrier
	s_add_i32 s64, 0, 0x18000
	s_add_i32 s65, 0, 0x1c000
	v_add_u32_e32 v140, s64, v161
	v_add_u32_e32 v174, s65, v161
	ds_read_b128 v[128:131], v140
	ds_read_b128 v[132:135], v140 offset:1024
	ds_read_b128 v[136:139], v140 offset:2048
	ds_read_b128 v[140:143], v140 offset:3072
	ds_read_b128 v[156:159], v174
	ds_read_b128 v[166:169], v174 offset:1024
	ds_read_b128 v[170:173], v174 offset:2048
	ds_read_b128 v[174:177], v174 offset:3072
	s_mov_b32 m0, s47
	s_nop 0
	global_load_lds_dwordx4 v146, s[40:41]
	s_add_u32 s40, s40, 0x40000
	s_addc_u32 s41, s41, 0
	s_mov_b32 m0, s48
	ds_read_b128 v[178:181], v165 offset:32768
	ds_read_b128 v[182:185], v165 offset:33792
	ds_read_b128 v[186:189], v165 offset:34816
	ds_read_b128 v[190:193], v165 offset:35840
	ds_read_b128 v[194:197], v165 offset:36864
	ds_read_b128 v[198:201], v165 offset:37888
	ds_read_b128 v[202:205], v165 offset:38912
	ds_read_b128 v[206:209], v165 offset:39936
	global_load_lds_dwordx4 v144, s[40:41]
	s_mov_b32 m0, s49
	s_nop 0
	global_load_lds_dwordx4 v146, s[40:41]
	s_waitcnt vmcnt(8)
	s_waitcnt lgkmcnt(0)
	s_barrier
	s_setprio 1
	s_waitcnt lgkmcnt(0)
	v_mfma_f32_16x16x32_bf16 v[124:127], v[128:131], v[178:181], v[124:127]
	v_mfma_f32_16x16x32_bf16 v[120:123], v[136:139], v[178:181], v[120:123]
	v_mfma_f32_16x16x32_bf16 v[116:119], v[128:131], v[186:189], v[116:119]
	v_mfma_f32_16x16x32_bf16 v[108:111], v[136:139], v[186:189], v[108:111]
	v_mfma_f32_16x16x32_bf16 v[96:99], v[128:131], v[194:197], v[96:99]
	v_mfma_f32_16x16x32_bf16 v[88:91], v[136:139], v[194:197], v[88:91]
	v_mfma_f32_16x16x32_bf16 v[84:87], v[128:131], v[202:205], v[84:87]
	v_mfma_f32_16x16x32_bf16 v[76:79], v[136:139], v[202:205], v[76:79]
	v_mfma_f32_16x16x32_bf16 v[124:127], v[132:135], v[182:185], v[124:127]
	v_mfma_f32_16x16x32_bf16 v[120:123], v[140:143], v[182:185], v[120:123]
	v_mfma_f32_16x16x32_bf16 v[116:119], v[132:135], v[190:193], v[116:119]
	v_mfma_f32_16x16x32_bf16 v[108:111], v[140:143], v[190:193], v[108:111]
	v_mfma_f32_16x16x32_bf16 v[96:99], v[132:135], v[198:201], v[96:99]
	v_mfma_f32_16x16x32_bf16 v[88:91], v[140:143], v[198:201], v[88:91]
	v_mfma_f32_16x16x32_bf16 v[84:87], v[132:135], v[206:209], v[84:87]
	v_mfma_f32_16x16x32_bf16 v[76:79], v[140:143], v[206:209], v[76:79]
	s_setprio 0
	s_setprio 1
	v_mfma_f32_16x16x32_bf16 v[112:115], v[156:159], v[178:181], v[112:115]
	v_mfma_f32_16x16x32_bf16 v[104:107], v[170:173], v[178:181], v[104:107]
	v_mfma_f32_16x16x32_bf16 v[100:103], v[156:159], v[186:189], v[100:103]
	v_mfma_f32_16x16x32_bf16 v[92:95], v[170:173], v[186:189], v[92:95]
	v_mfma_f32_16x16x32_bf16 v[80:83], v[156:159], v[194:197], v[80:83]
	v_mfma_f32_16x16x32_bf16 v[72:75], v[170:173], v[194:197], v[72:75]
	v_mfma_f32_16x16x32_bf16 v[68:71], v[156:159], v[202:205], v[68:71]
	v_mfma_f32_16x16x32_bf16 v[64:67], v[170:173], v[202:205], v[64:67]
	v_mfma_f32_16x16x32_bf16 v[112:115], v[166:169], v[182:185], v[112:115]
	v_mfma_f32_16x16x32_bf16 v[104:107], v[174:177], v[182:185], v[104:107]
	v_mfma_f32_16x16x32_bf16 v[100:103], v[166:169], v[190:193], v[100:103]
	v_mfma_f32_16x16x32_bf16 v[92:95], v[174:177], v[190:193], v[92:95]
	v_mfma_f32_16x16x32_bf16 v[80:83], v[166:169], v[198:201], v[80:83]
	v_mfma_f32_16x16x32_bf16 v[72:75], v[174:177], v[198:201], v[72:75]
	v_mfma_f32_16x16x32_bf16 v[68:71], v[166:169], v[206:209], v[68:71]
	v_mfma_f32_16x16x32_bf16 v[64:67], v[174:177], v[206:209], v[64:67]
	s_setprio 0
	s_barrier
	s_add_i32 s40, s64, s46
	s_mov_b32 m0, s40
	ds_read_b128 v[178:181], v165 offset:49152
	ds_read_b128 v[182:185], v165 offset:50176
	ds_read_b128 v[186:189], v165 offset:51200
	ds_read_b128 v[190:193], v165 offset:52224
	ds_read_b128 v[194:197], v165 offset:53248
	ds_read_b128 v[198:201], v165 offset:54272
	ds_read_b128 v[202:205], v165 offset:55296
	ds_read_b128 v[206:209], v165 offset:56320
	s_add_u32 s38, s38, 0x80
	s_addc_u32 s39, s39, 0
	global_load_lds_dwordx4 v144, s[38:39]
	s_add_i32 m0, s40, 0x2000
	s_add_i32 s40, s65, s46
	global_load_lds_dwordx4 v146, s[38:39]
	s_add_u32 s38, s38, 0x40000
	s_addc_u32 s39, s39, 0
	s_mov_b32 m0, s40
	s_nop 0
	global_load_lds_dwordx4 v144, s[38:39]
	s_add_i32 m0, s40, 0x2000
	s_nop 0
	global_load_lds_dwordx4 v146, s[38:39]
	s_mov_b32 m0, s52
	s_nop 0
	global_load_lds_dwordx4 v144, s[68:69]
	s_mov_b32 m0, s53
	s_nop 0
	global_load_lds_dwordx4 v146, s[68:69]
	s_waitcnt vmcnt(8)
	s_waitcnt lgkmcnt(0)
	s_barrier
	s_setprio 1
	s_waitcnt lgkmcnt(0)
	v_mfma_f32_16x16x32_bf16 v[60:63], v[128:131], v[178:181], v[60:63]
	v_mfma_f32_16x16x32_bf16 v[56:59], v[136:139], v[178:181], v[56:59]
	v_mfma_f32_16x16x32_bf16 v[52:55], v[128:131], v[186:189], v[52:55]
	v_mfma_f32_16x16x32_bf16 v[44:47], v[136:139], v[186:189], v[44:47]
	v_mfma_f32_16x16x32_bf16 v[36:39], v[128:131], v[194:197], v[36:39]
	v_mfma_f32_16x16x32_bf16 v[28:31], v[136:139], v[194:197], v[28:31]
	v_mfma_f32_16x16x32_bf16 v[20:23], v[128:131], v[202:205], v[20:23]
	v_mfma_f32_16x16x32_bf16 v[12:15], v[136:139], v[202:205], v[12:15]
	v_mfma_f32_16x16x32_bf16 v[60:63], v[132:135], v[182:185], v[60:63]
	v_mfma_f32_16x16x32_bf16 v[56:59], v[140:143], v[182:185], v[56:59]
	v_mfma_f32_16x16x32_bf16 v[52:55], v[132:135], v[190:193], v[52:55]
	v_mfma_f32_16x16x32_bf16 v[44:47], v[140:143], v[190:193], v[44:47]
	v_mfma_f32_16x16x32_bf16 v[36:39], v[132:135], v[198:201], v[36:39]
	v_mfma_f32_16x16x32_bf16 v[28:31], v[140:143], v[198:201], v[28:31]
	v_mfma_f32_16x16x32_bf16 v[20:23], v[132:135], v[206:209], v[20:23]
	v_mfma_f32_16x16x32_bf16 v[12:15], v[140:143], v[206:209], v[12:15]
	s_setprio 0
	s_setprio 1
	v_mfma_f32_16x16x32_bf16 v[48:51], v[156:159], v[178:181], v[48:51]
	v_mfma_f32_16x16x32_bf16 v[40:43], v[170:173], v[178:181], v[40:43]
	v_mfma_f32_16x16x32_bf16 v[32:35], v[156:159], v[186:189], v[32:35]
	v_mfma_f32_16x16x32_bf16 v[24:27], v[170:173], v[186:189], v[24:27]
	v_mfma_f32_16x16x32_bf16 v[16:19], v[156:159], v[194:197], v[16:19]
	s_add_i32 s63, s63, 2
	v_mfma_f32_16x16x32_bf16 v[8:11], v[170:173], v[194:197], v[8:11]
	v_mfma_f32_16x16x32_bf16 v[4:7], v[156:159], v[202:205], v[4:7]
	s_add_u32 s36, s36, 0x100
	s_addc_u32 s37, s37, 0
	v_mfma_f32_16x16x32_bf16 v[0:3], v[170:173], v[202:205], v[0:3]
	v_mfma_f32_16x16x32_bf16 v[48:51], v[166:169], v[182:185], v[48:51]
	s_add_u32 s61, s61, 0x100
	s_addc_u32 s62, s62, 0
	v_mfma_f32_16x16x32_bf16 v[40:43], v[174:177], v[182:185], v[40:43]
	v_mfma_f32_16x16x32_bf16 v[32:35], v[166:169], v[190:193], v[32:35]
	s_cmp_gt_u32 s63, 13
	v_mfma_f32_16x16x32_bf16 v[24:27], v[174:177], v[190:193], v[24:27]
	v_mfma_f32_16x16x32_bf16 v[16:19], v[166:169], v[198:201], v[16:19]
	v_mfma_f32_16x16x32_bf16 v[8:11], v[174:177], v[198:201], v[8:11]
	v_mfma_f32_16x16x32_bf16 v[4:7], v[166:169], v[206:209], v[4:7]
	v_mfma_f32_16x16x32_bf16 v[0:3], v[174:177], v[206:209], v[0:3]
	s_setprio 0
	s_barrier
	s_cbranch_scc0 .LBB0_766
	s_and_b64 vcc, exec, s[12:13]
	s_cbranch_vccz .LBB0_769
	s_barrier
